# in-proj: tiles of the last partial round split along K over workgroup pairs with f32 partial hand-over (same mechanism as MLP-up) (on v86)
# baseline (speedup 1.0000x reference)
.LBB0_36:
	s_cmp_eq_u32 s2, 0
	s_cselect_b64 s[4:5], -1, 0
	v_cmp_gt_u32_e32 vcc, 64, v164
	s_and_b64 s[8:9], s[4:5], vcc
	s_and_saveexec_b64 s[6:7], s[8:9]
	s_cbranch_execz .LBB0_38
	v_lshlrev_b32_e32 v1, 2, v164
	v_mov_b32_e32 v2, 0
	global_store_dword v1, v2, s[76:77]
	global_store_dword v1, v2, s[76:77] offset:2048
	global_store_dword v1, v2, s[76:77] offset:256
	global_store_dword v1, v2, s[76:77] offset:512

.LBB0_78:
	s_and_b32 s45, s6, 3
	v_readlane_b32 s16, v254, 57
	s_lshl_b32 s6, s7, 13
	s_lshl_b32 s38, s45, 12
	v_readlane_b32 s17, v254, 58
	s_and_b64 s[16:17], s[16:17], exec
	v_readlane_b32 s16, v252, 18
	v_readlane_b32 s17, v252, 19
	v_readlane_b32 s39, v252, 42
	s_cselect_b32 s85, s17, s39
	v_readlane_b32 s17, v252, 41
	s_cselect_b32 s84, s16, s17
	s_cselect_b32 s16, 0, 0x11000
	s_add_u32 s86, s41, s16
	v_readlane_b32 s16, v252, 17
	s_addc_u32 s87, s16, 0
	s_add_i32 m0, s97, 0x18000
	v_lshl_add_u64 v[8:9], v[8:9], 0, s[26:27]
	s_waitcnt vmcnt(2)
	s_barrier
	global_load_lds_dwordx4 v[8:9], off
	v_lshl_add_u64 v[6:7], v[6:7], 0, s[26:27]
	s_add_i32 m0, s97, 0x1a000
	s_add_i32 s60, s97, 0x8000
	s_add_i32 s61, s97, 0xa000
	global_load_lds_dwordx4 v[6:7], off
	v_lshl_add_u64 v[2:3], v[2:3], 0, s[26:27]
	s_mov_b32 m0, s60
	s_add_u32 s16, s8, 0x80080
	global_load_lds_dwordx4 v[2:3], off
	v_lshl_add_u64 v[2:3], v[4:5], 0, s[26:27]
	s_mov_b32 m0, s61
	s_addc_u32 s17, s9, 0
	global_load_lds_dwordx4 v[2:3], off
	s_add_i32 m0, s97, 0x1c000
	v_lshl_add_u64 v[2:3], s[16:17], 0, v[156:157]
	global_load_lds_dwordx4 v[2:3], off
	v_lshl_add_u64 v[2:3], s[16:17], 0, v[160:161]
	s_add_i32 m0, s97, 0x1e000
	s_cmpk_lt_u32 s40, 0x100
	global_load_lds_dwordx4 v[2:3], off
	v_bfe_u32 v3, v1, 4, 2
	v_and_b32_e32 v2, 15, v1
	v_lshlrev_b32_e32 v5, 4, v3
	v_lshlrev_b32_e32 v1, 2, v1
	v_lshl_or_b32 v5, v2, 6, v5
	v_and_b32_e32 v1, 32, v1
	v_bitop3_b32 v6, v5, s6, v1 bitop3:0xde
	v_bitop3_b32 v169, v5, s38, v1 bitop3:0xde
	v_or_b32_e32 v1, v3, v2
	v_cmp_eq_u32_e64 s[38:39], 0, v1
	v_lshlrev_b32_e32 v1, 15, v10
	v_and_b32_e32 v1, 0xffff0000, v1
	v_lshl_or_b32 v167, s7, 6, v2
	v_lshl_add_u32 v1, v11, 12, v1
	v_and_b32_e32 v2, 1, v10
	s_cselect_b64 s[16:17], -1, 0
	s_lshr_b32 s6, s40, 4
	v_lshl_or_b32 v1, v2, 6, v1
	s_and_b32 s6, s6, 4
	v_lshl_add_u32 v162, v12, 1, v1
	v_lshlrev_b32_e32 v1, 15, v13
	s_add_u32 s6, s4, s6
	v_and_b32_e32 v1, 0xffff0000, v1
	s_waitcnt vmcnt(6)
	v_writelane_b32 v255, s45, 20
	s_addc_u32 s7, s5, 0
	v_lshl_add_u32 v1, v14, 12, v1
	v_and_b32_e32 v2, 1, v13
	v_lshlrev_b32_e32 v4, 3, v3
	v_writelane_b32 v255, s6, 21
	s_cmp_lg_u64 s[4:5], 0
	v_lshl_or_b32 v1, v2, 6, v1
	s_mov_b32 s62, 0
	s_mov_b32 s98, 0
	v_lshl_or_b32 v213, s45, 5, v4
	v_writelane_b32 v255, s7, 22
	s_cselect_b64 s[92:93], -1, 0
	v_mov_b32_e32 v163, v0
	v_lshl_add_u32 v184, v15, 1, v1
	v_mov_b32_e32 v185, v0
	v_add_u32_e32 v214, 0, v6
	s_barrier
	s_branch .LBB0_81

.LBB0_80:
	s_andn2_b64 vcc, exec, s[8:9]
	s_mov_b32 s64, s63
	s_mov_b32 s98, s99
	s_mov_b32 s44, s94
	s_mov_b32 s96, s6
	s_mov_b64 s[8:9], s[4:5]
	s_mov_b64 s[42:43], s[46:47]
	s_cbranch_vccz .LBB0_191
.LBB0_81:
	s_add_i32 s62, s62, 1
	s_mul_i32 s4, s62, s31
	s_mul_hi_u32 s5, s62, s82
	s_add_i32 s5, s5, s4
	s_mul_i32 s4, s62, s82
	s_add_u32 s4, s4, s2
	s_addc_u32 s5, s5, s3
	s_waitcnt lgkmcnt(0)
	s_mov_b32 s99, 0
	s_add_i32 s100, s88, -1
	s_lshr_b32 s100, s100, 8
	s_cmp_lg_u32 s62, s100
	s_cbranch_scc1 .Lmy_ik_nosplit
	s_lshl_b32 s101, s100, 8
	s_sub_i32 s100, s88, s101
	s_lshl_b32 s100, s100, 1
	s_mov_b32 s4, s88
	s_cmp_lt_u32 s2, s100
	s_cbranch_scc0 .Lmy_ik_nosplit
	s_lshr_b32 s4, s2, 1
	s_add_i32 s4, s4, s101
	s_and_b32 s99, s2, 1
	s_add_i32 s99, s99, 1
.Lmy_ik_nosplit:
	v_mov_b64_e32 v[2:3], s[88:89]
	v_cmp_ge_i64_e32 vcc, s[4:5], v[2:3]
	v_cmp_lt_i64_e64 s[40:41], s[4:5], v[2:3]
	s_cbranch_vccnz .LBB0_90
	s_cmp_lt_i32 s4, s56
	s_cbranch_scc1 .LBB0_84
	s_sub_i32 s4, s4, s56
	s_mov_b32 s63, 1
	s_mov_b32 s7, 33
	s_mul_i32 s5, s49, 33
	s_mov_b32 s6, s49
	s_branch .LBB0_85

.LBB0_90:
	s_ashr_i32 s7, s6, 31
	s_lshl_b64 s[4:5], s[6:7], 20
	s_cmp_eq_u32 s63, 0
	s_cselect_b32 s45, s80, s54
	s_cselect_b32 s7, s81, s37
	s_cselect_b32 s65, s59, s80
	s_cselect_b32 s66, s58, s81
	s_add_u32 s46, s45, s4
	s_addc_u32 s47, s7, s5
	s_cmp_eq_u32 s99, 2
	s_cselect_b32 s100, 0x800, 0
	s_add_u32 s46, s46, s100
	s_addc_u32 s47, s47, 0
	s_and_b64 s[4:5], s[40:41], exec
	s_cselect_b32 s7, s47, s43
	s_cselect_b32 s45, s46, s42
	s_ashr_i32 s95, s94, 31
	s_lshl_b64 s[4:5], s[94:95], 20
	s_add_u32 s4, s65, s4
	s_addc_u32 s5, s66, s5
	s_add_u32 s4, s4, s100
	s_addc_u32 s5, s5, 0
	s_and_b64 s[66:67], s[40:41], exec
	s_cselect_b32 s65, s5, s9
	s_cselect_b32 s66, s4, s8
	s_add_u32 s42, s42, 0x80080
	s_addc_u32 s43, s43, 0
	s_add_u32 s67, s8, 0x100
	v_mov_b32_e32 v2, 0
	s_addc_u32 s68, s9, 0
	s_cmp_eq_u32 s98, 0
	s_cselect_b32 s69, -2, 14
	v_mov_b32_e32 v3, v2
	v_mov_b32_e32 v4, v2
	v_mov_b32_e32 v5, v2
	v_mov_b32_e32 v6, v2
	v_mov_b32_e32 v7, v2
	v_mov_b32_e32 v8, v2
	v_mov_b32_e32 v9, v2
	v_mov_b32_e32 v18, v2
	v_mov_b32_e32 v19, v2
	v_mov_b32_e32 v20, v2
	v_mov_b32_e32 v21, v2
	v_mov_b32_e32 v22, v2
	v_mov_b32_e32 v23, v2
	v_mov_b32_e32 v24, v2
	v_mov_b32_e32 v25, v2
	v_mov_b32_e32 v34, v2
	v_mov_b32_e32 v35, v2
	v_mov_b32_e32 v36, v2
	v_mov_b32_e32 v37, v2
	v_mov_b32_e32 v38, v2
	v_mov_b32_e32 v39, v2
	v_mov_b32_e32 v40, v2
	v_mov_b32_e32 v41, v2
	v_mov_b32_e32 v50, v2
	v_mov_b32_e32 v51, v2
	v_mov_b32_e32 v52, v2
	v_mov_b32_e32 v53, v2
	v_mov_b32_e32 v54, v2
	v_mov_b32_e32 v55, v2
	v_mov_b32_e32 v56, v2
	v_mov_b32_e32 v57, v2
	v_mov_b32_e32 v10, v2
	v_mov_b32_e32 v11, v2
	v_mov_b32_e32 v12, v2
	v_mov_b32_e32 v13, v2
	v_mov_b32_e32 v14, v2
	v_mov_b32_e32 v15, v2
	v_mov_b32_e32 v16, v2
	v_mov_b32_e32 v17, v2
	v_mov_b32_e32 v26, v2
	v_mov_b32_e32 v27, v2
	v_mov_b32_e32 v28, v2
	v_mov_b32_e32 v29, v2
	v_mov_b32_e32 v30, v2
	v_mov_b32_e32 v31, v2
	v_mov_b32_e32 v32, v2
	v_mov_b32_e32 v33, v2
	v_mov_b32_e32 v42, v2
	v_mov_b32_e32 v43, v2
	v_mov_b32_e32 v44, v2
	v_mov_b32_e32 v45, v2
	v_mov_b32_e32 v46, v2
	v_mov_b32_e32 v47, v2
	v_mov_b32_e32 v48, v2
	v_mov_b32_e32 v49, v2
	v_mov_b32_e32 v58, v2
	v_mov_b32_e32 v59, v2
	v_mov_b32_e32 v60, v2
	v_mov_b32_e32 v61, v2
	v_mov_b32_e32 v62, v2
	v_mov_b32_e32 v63, v2
	v_mov_b32_e32 v64, v2
	v_mov_b32_e32 v65, v2
	v_mov_b32_e32 v66, v2
	v_mov_b32_e32 v67, v2
	v_mov_b32_e32 v68, v2
	v_mov_b32_e32 v69, v2
	v_mov_b32_e32 v70, v2
	v_mov_b32_e32 v71, v2
	v_mov_b32_e32 v72, v2
	v_mov_b32_e32 v73, v2
	v_mov_b32_e32 v82, v2
	v_mov_b32_e32 v83, v2
	v_mov_b32_e32 v84, v2
	v_mov_b32_e32 v85, v2
	v_mov_b32_e32 v86, v2
	v_mov_b32_e32 v87, v2
	v_mov_b32_e32 v88, v2
	v_mov_b32_e32 v89, v2
	v_mov_b32_e32 v98, v2
	v_mov_b32_e32 v99, v2
	v_mov_b32_e32 v100, v2
	v_mov_b32_e32 v101, v2
	v_mov_b32_e32 v102, v2
	v_mov_b32_e32 v103, v2
	v_mov_b32_e32 v104, v2
	v_mov_b32_e32 v105, v2
	v_mov_b32_e32 v120, v2
	v_mov_b32_e32 v121, v2
	v_mov_b32_e32 v122, v2
	v_mov_b32_e32 v123, v2
	v_mov_b32_e32 v124, v2
	v_mov_b32_e32 v125, v2
	v_mov_b32_e32 v126, v2
	v_mov_b32_e32 v127, v2
	v_mov_b32_e32 v74, v2
	v_mov_b32_e32 v75, v2
	v_mov_b32_e32 v76, v2
	v_mov_b32_e32 v77, v2
	v_mov_b32_e32 v78, v2
	v_mov_b32_e32 v79, v2
	v_mov_b32_e32 v80, v2
	v_mov_b32_e32 v81, v2
	v_mov_b32_e32 v90, v2
	v_mov_b32_e32 v91, v2
	v_mov_b32_e32 v92, v2
	v_mov_b32_e32 v93, v2
	v_mov_b32_e32 v94, v2
	v_mov_b32_e32 v95, v2
	v_mov_b32_e32 v96, v2
	v_mov_b32_e32 v97, v2
	v_mov_b32_e32 v106, v2
	v_mov_b32_e32 v107, v2
	v_mov_b32_e32 v108, v2
	v_mov_b32_e32 v109, v2
	v_mov_b32_e32 v116, v2
	v_mov_b32_e32 v117, v2
	v_mov_b32_e32 v118, v2
	v_mov_b32_e32 v119, v2
	v_mov_b32_e32 v128, v2
	v_mov_b32_e32 v129, v2
	v_mov_b32_e32 v130, v2
	v_mov_b32_e32 v131, v2
	v_mov_b32_e32 v132, v2
	v_mov_b32_e32 v133, v2
	v_mov_b32_e32 v134, v2
	v_mov_b32_e32 v135, v2
.LBB0_91:
	s_add_u32 s8, s42, 0xfff80080
	s_addc_u32 s9, s43, -1
	s_add_i32 s70, 0, 0x10000
	s_cmp_eq_u32 s69, 28
	s_cselect_b32 vcc_hi, s7, s9
	s_cselect_b32 vcc_lo, s45, s8
	v_add_u32_e32 v1, s70, v169
	s_cselect_b32 s9, s65, s68
	s_cselect_b32 s8, s66, s67
	s_add_i32 s72, 0, 0x14000
	ds_read_b128 v[136:139], v1
	ds_read_b128 v[140:143], v1 offset:1024
	ds_read_b128 v[144:147], v1 offset:2048
	ds_read_b128 v[148:151], v1 offset:3072
	v_add_u32_e32 v1, s72, v169
	ds_read_b128 v[152:155], v1
	ds_read_b128 v[186:189], v1 offset:1024
	ds_read_b128 v[190:193], v1 offset:2048
	ds_read_b128 v[194:197], v1 offset:3072
	v_lshl_add_u64 v[170:171], s[42:43], 0, v[162:163]
	s_add_i32 m0, s97, 0xc000
	ds_read_b128 v[198:201], v214
	ds_read_b128 v[216:219], v214 offset:1024
	ds_read_b128 v[220:223], v214 offset:2048
	ds_read_b128 v[224:227], v214 offset:3072
	ds_read_b128 v[228:231], v214 offset:4096
	ds_read_b128 v[232:235], v214 offset:5120
	ds_read_b128 v[236:239], v214 offset:6144
	ds_read_b128 v[240:243], v214 offset:7168
	global_load_lds_dwordx4 v[170:171], off
	v_lshl_add_u64 v[170:171], s[42:43], 0, v[184:185]
	s_add_i32 m0, s97, 0xe000
	s_nop 0
	global_load_lds_dwordx4 v[170:171], off
	s_waitcnt vmcnt(8)
	s_waitcnt lgkmcnt(0)
	s_barrier
	s_setprio 1
	v_mfma_f32_16x16x32_bf16 v[132:135], v[136:139], v[198:201], v[132:135]
	v_mfma_f32_16x16x32_bf16 v[128:131], v[144:147], v[198:201], v[128:131]
	v_mfma_f32_16x16x32_bf16 v[116:119], v[136:139], v[220:223], v[116:119]
	v_mfma_f32_16x16x32_bf16 v[106:109], v[144:147], v[220:223], v[106:109]
	v_mfma_f32_16x16x32_bf16 v[94:97], v[136:139], v[228:231], v[94:97]
	v_mfma_f32_16x16x32_bf16 v[90:93], v[144:147], v[228:231], v[90:93]
	v_mfma_f32_16x16x32_bf16 v[78:81], v[136:139], v[236:239], v[78:81]
	v_mfma_f32_16x16x32_bf16 v[74:77], v[144:147], v[236:239], v[74:77]
	v_mfma_f32_16x16x32_bf16 v[132:135], v[140:143], v[216:219], v[132:135]
	v_mfma_f32_16x16x32_bf16 v[128:131], v[148:151], v[216:219], v[128:131]
	v_mfma_f32_16x16x32_bf16 v[116:119], v[140:143], v[224:227], v[116:119]
	v_mfma_f32_16x16x32_bf16 v[106:109], v[148:151], v[224:227], v[106:109]
	v_mfma_f32_16x16x32_bf16 v[94:97], v[140:143], v[232:235], v[94:97]
	v_mfma_f32_16x16x32_bf16 v[90:93], v[148:151], v[232:235], v[90:93]
	v_mfma_f32_16x16x32_bf16 v[78:81], v[140:143], v[240:243], v[78:81]
	v_mfma_f32_16x16x32_bf16 v[74:77], v[148:151], v[240:243], v[74:77]
	v_mfma_f32_16x16x32_bf16 v[124:127], v[152:155], v[198:201], v[124:127]
	v_mfma_f32_16x16x32_bf16 v[120:123], v[190:193], v[198:201], v[120:123]
	v_mfma_f32_16x16x32_bf16 v[102:105], v[152:155], v[220:223], v[102:105]
	v_mfma_f32_16x16x32_bf16 v[98:101], v[190:193], v[220:223], v[98:101]
	v_mfma_f32_16x16x32_bf16 v[86:89], v[152:155], v[228:231], v[86:89]
	v_mfma_f32_16x16x32_bf16 v[82:85], v[190:193], v[228:231], v[82:85]
	v_mfma_f32_16x16x32_bf16 v[70:73], v[152:155], v[236:239], v[70:73]
	v_mfma_f32_16x16x32_bf16 v[66:69], v[190:193], v[236:239], v[66:69]
	v_mfma_f32_16x16x32_bf16 v[124:127], v[186:189], v[216:219], v[124:127]
	v_mfma_f32_16x16x32_bf16 v[120:123], v[194:197], v[216:219], v[120:123]
	v_mfma_f32_16x16x32_bf16 v[102:105], v[186:189], v[224:227], v[102:105]
	v_mfma_f32_16x16x32_bf16 v[98:101], v[194:197], v[224:227], v[98:101]
	v_mfma_f32_16x16x32_bf16 v[86:89], v[186:189], v[232:235], v[86:89]
	v_mfma_f32_16x16x32_bf16 v[82:85], v[194:197], v[232:235], v[82:85]
	v_mfma_f32_16x16x32_bf16 v[70:73], v[186:189], v[240:243], v[70:73]
	v_mfma_f32_16x16x32_bf16 v[66:69], v[194:197], v[240:243], v[66:69]
	s_setprio 0
	s_barrier
	s_add_i32 s70, s70, s57
	v_lshl_add_u64 v[170:171], s[8:9], 0, v[156:157]
	s_mov_b32 m0, s70
	ds_read_b128 v[198:201], v214 offset:16384
	ds_read_b128 v[216:219], v214 offset:17408
	ds_read_b128 v[220:223], v214 offset:18432
	ds_read_b128 v[224:227], v214 offset:19456
	ds_read_b128 v[228:231], v214 offset:20480
	ds_read_b128 v[232:235], v214 offset:21504
	ds_read_b128 v[236:239], v214 offset:22528
	ds_read_b128 v[240:243], v214 offset:23552
	global_load_lds_dwordx4 v[170:171], off
	s_add_i32 m0, s70, 0x2000
	s_add_u32 s70, s8, 0x80000
	v_lshl_add_u64 v[172:173], s[8:9], 0, v[160:161]
	s_addc_u32 s71, s9, 0
	s_add_i32 s72, s72, s57
	global_load_lds_dwordx4 v[172:173], off
	v_lshl_add_u64 v[244:245], s[70:71], 0, v[156:157]
	s_mov_b32 m0, s72
	v_lshl_add_u64 v[246:247], vcc, 0, v[158:159]
	global_load_lds_dwordx4 v[244:245], off
	v_lshl_add_u64 v[244:245], s[70:71], 0, v[160:161]
	s_add_i32 m0, s72, 0x2000
	s_nop 0
	global_load_lds_dwordx4 v[244:245], off
	v_lshl_add_u64 v[244:245], vcc, 0, v[110:111]
	s_mov_b32 m0, s97
	s_nop 0
	global_load_lds_dwordx4 v[244:245], off
	s_mov_b32 m0, s35
	s_nop 0
	global_load_lds_dwordx4 v[246:247], off
	s_waitcnt vmcnt(8)
	s_waitcnt lgkmcnt(0)
	s_barrier
	s_setprio 1
	v_mfma_f32_16x16x32_bf16 v[62:65], v[136:139], v[198:201], v[62:65]
	v_mfma_f32_16x16x32_bf16 v[58:61], v[144:147], v[198:201], v[58:61]
	v_mfma_f32_16x16x32_bf16 v[46:49], v[136:139], v[220:223], v[46:49]
	v_mfma_f32_16x16x32_bf16 v[42:45], v[144:147], v[220:223], v[42:45]
	v_mfma_f32_16x16x32_bf16 v[30:33], v[136:139], v[228:231], v[30:33]
	v_mfma_f32_16x16x32_bf16 v[26:29], v[144:147], v[228:231], v[26:29]
	v_mfma_f32_16x16x32_bf16 v[14:17], v[136:139], v[236:239], v[14:17]
	v_mfma_f32_16x16x32_bf16 v[10:13], v[144:147], v[236:239], v[10:13]
	v_mfma_f32_16x16x32_bf16 v[62:65], v[140:143], v[216:219], v[62:65]
	v_mfma_f32_16x16x32_bf16 v[58:61], v[148:151], v[216:219], v[58:61]
	v_mfma_f32_16x16x32_bf16 v[46:49], v[140:143], v[224:227], v[46:49]
	v_mfma_f32_16x16x32_bf16 v[42:45], v[148:151], v[224:227], v[42:45]
	v_mfma_f32_16x16x32_bf16 v[30:33], v[140:143], v[232:235], v[30:33]
	v_mfma_f32_16x16x32_bf16 v[26:29], v[148:151], v[232:235], v[26:29]
	v_mfma_f32_16x16x32_bf16 v[14:17], v[140:143], v[240:243], v[14:17]
	v_mfma_f32_16x16x32_bf16 v[10:13], v[148:151], v[240:243], v[10:13]
	v_mfma_f32_16x16x32_bf16 v[54:57], v[152:155], v[198:201], v[54:57]
	v_mfma_f32_16x16x32_bf16 v[50:53], v[190:193], v[198:201], v[50:53]
	v_mfma_f32_16x16x32_bf16 v[38:41], v[152:155], v[220:223], v[38:41]
	v_mfma_f32_16x16x32_bf16 v[34:37], v[190:193], v[220:223], v[34:37]
	v_mfma_f32_16x16x32_bf16 v[22:25], v[152:155], v[228:231], v[22:25]
	v_mfma_f32_16x16x32_bf16 v[18:21], v[190:193], v[228:231], v[18:21]
	v_mfma_f32_16x16x32_bf16 v[6:9], v[152:155], v[236:239], v[6:9]
	v_mfma_f32_16x16x32_bf16 v[2:5], v[190:193], v[236:239], v[2:5]
	v_mfma_f32_16x16x32_bf16 v[54:57], v[186:189], v[216:219], v[54:57]
	v_mfma_f32_16x16x32_bf16 v[50:53], v[194:197], v[216:219], v[50:53]
	v_mfma_f32_16x16x32_bf16 v[38:41], v[186:189], v[224:227], v[38:41]
	v_mfma_f32_16x16x32_bf16 v[34:37], v[194:197], v[224:227], v[34:37]
	v_mfma_f32_16x16x32_bf16 v[22:25], v[186:189], v[232:235], v[22:25]
	v_mfma_f32_16x16x32_bf16 v[18:21], v[194:197], v[232:235], v[18:21]
	v_mfma_f32_16x16x32_bf16 v[6:9], v[186:189], v[240:243], v[6:9]
	v_mfma_f32_16x16x32_bf16 v[2:5], v[194:197], v[240:243], v[2:5]
	s_setprio 0
	s_barrier
	s_add_i32 s72, 0, 0x18000
	v_add_u32_e32 v1, s72, v169
	s_add_i32 s73, 0, 0x1c000
	ds_read_b128 v[136:139], v1
	ds_read_b128 v[140:143], v1 offset:1024
	ds_read_b128 v[144:147], v1 offset:2048
	ds_read_b128 v[148:151], v1 offset:3072
	v_add_u32_e32 v1, s73, v169
	ds_read_b128 v[152:155], v1
	ds_read_b128 v[186:189], v1 offset:1024
	ds_read_b128 v[190:193], v1 offset:2048
	ds_read_b128 v[194:197], v1 offset:3072
	s_add_u32 s70, vcc_lo, 0x80000
	s_addc_u32 s71, vcc_hi, 0
	s_mov_b32 m0, s55
	v_lshl_add_u64 v[248:249], s[70:71], 0, v[110:111]
	ds_read_b128 v[198:201], v214 offset:32768
	ds_read_b128 v[216:219], v214 offset:33792
	ds_read_b128 v[220:223], v214 offset:34816
	ds_read_b128 v[224:227], v214 offset:35840
	ds_read_b128 v[228:231], v214 offset:36864
	ds_read_b128 v[232:235], v214 offset:37888
	ds_read_b128 v[236:239], v214 offset:38912
	ds_read_b128 v[240:243], v214 offset:39936
	global_load_lds_dwordx4 v[248:249], off
	v_lshl_add_u64 v[248:249], s[70:71], 0, v[158:159]
	s_mov_b32 m0, s34
	s_nop 0
	global_load_lds_dwordx4 v[248:249], off
	s_waitcnt vmcnt(8)
	s_waitcnt lgkmcnt(0)
	s_barrier
	s_setprio 1
	v_mfma_f32_16x16x32_bf16 v[132:135], v[136:139], v[198:201], v[132:135]
	v_mfma_f32_16x16x32_bf16 v[128:131], v[144:147], v[198:201], v[128:131]
	v_mfma_f32_16x16x32_bf16 v[116:119], v[136:139], v[220:223], v[116:119]
	v_mfma_f32_16x16x32_bf16 v[106:109], v[144:147], v[220:223], v[106:109]
	v_mfma_f32_16x16x32_bf16 v[94:97], v[136:139], v[228:231], v[94:97]
	v_mfma_f32_16x16x32_bf16 v[90:93], v[144:147], v[228:231], v[90:93]
	v_mfma_f32_16x16x32_bf16 v[78:81], v[136:139], v[236:239], v[78:81]
	v_mfma_f32_16x16x32_bf16 v[74:77], v[144:147], v[236:239], v[74:77]
	v_mfma_f32_16x16x32_bf16 v[132:135], v[140:143], v[216:219], v[132:135]
	v_mfma_f32_16x16x32_bf16 v[128:131], v[148:151], v[216:219], v[128:131]
	v_mfma_f32_16x16x32_bf16 v[116:119], v[140:143], v[224:227], v[116:119]
	v_mfma_f32_16x16x32_bf16 v[106:109], v[148:151], v[224:227], v[106:109]
	v_mfma_f32_16x16x32_bf16 v[94:97], v[140:143], v[232:235], v[94:97]
	v_mfma_f32_16x16x32_bf16 v[90:93], v[148:151], v[232:235], v[90:93]
	v_mfma_f32_16x16x32_bf16 v[78:81], v[140:143], v[240:243], v[78:81]
	v_mfma_f32_16x16x32_bf16 v[74:77], v[148:151], v[240:243], v[74:77]
	v_mfma_f32_16x16x32_bf16 v[124:127], v[152:155], v[198:201], v[124:127]
	v_mfma_f32_16x16x32_bf16 v[120:123], v[190:193], v[198:201], v[120:123]
	v_mfma_f32_16x16x32_bf16 v[102:105], v[152:155], v[220:223], v[102:105]
	v_mfma_f32_16x16x32_bf16 v[98:101], v[190:193], v[220:223], v[98:101]
	v_mfma_f32_16x16x32_bf16 v[86:89], v[152:155], v[228:231], v[86:89]
	v_mfma_f32_16x16x32_bf16 v[82:85], v[190:193], v[228:231], v[82:85]
	v_mfma_f32_16x16x32_bf16 v[70:73], v[152:155], v[236:239], v[70:73]
	v_mfma_f32_16x16x32_bf16 v[66:69], v[190:193], v[236:239], v[66:69]
	v_mfma_f32_16x16x32_bf16 v[124:127], v[186:189], v[216:219], v[124:127]
	v_mfma_f32_16x16x32_bf16 v[120:123], v[194:197], v[216:219], v[120:123]
	v_mfma_f32_16x16x32_bf16 v[102:105], v[186:189], v[224:227], v[102:105]
	v_mfma_f32_16x16x32_bf16 v[98:101], v[194:197], v[224:227], v[98:101]
	v_mfma_f32_16x16x32_bf16 v[86:89], v[186:189], v[232:235], v[86:89]
	v_mfma_f32_16x16x32_bf16 v[82:85], v[194:197], v[232:235], v[82:85]
	v_mfma_f32_16x16x32_bf16 v[70:73], v[186:189], v[240:243], v[70:73]
	v_mfma_f32_16x16x32_bf16 v[66:69], v[194:197], v[240:243], v[66:69]
	s_setprio 0
	s_barrier
	s_add_i32 s70, s72, s57
	v_lshl_add_u64 v[170:171], v[170:171], 0, s[26:27]
	s_mov_b32 m0, s70
	ds_read_b128 v[198:201], v214 offset:49152
	ds_read_b128 v[216:219], v214 offset:50176
	ds_read_b128 v[220:223], v214 offset:51200
	ds_read_b128 v[224:227], v214 offset:52224
	ds_read_b128 v[228:231], v214 offset:53248
	ds_read_b128 v[232:235], v214 offset:54272
	ds_read_b128 v[236:239], v214 offset:55296
	ds_read_b128 v[240:243], v214 offset:56320
	global_load_lds_dwordx4 v[170:171], off
	s_add_i32 m0, s70, 0x2000
	s_add_u32 s8, s8, 0x80080
	v_lshl_add_u64 v[170:171], v[172:173], 0, s[26:27]
	s_addc_u32 s9, s9, 0
	s_add_i32 s70, s73, s57
	global_load_lds_dwordx4 v[170:171], off
	v_lshl_add_u64 v[170:171], s[8:9], 0, v[156:157]
	s_mov_b32 m0, s70
	s_nop 0
	global_load_lds_dwordx4 v[170:171], off
	v_lshl_add_u64 v[170:171], s[8:9], 0, v[160:161]
	s_add_i32 m0, s70, 0x2000
	s_nop 0
	global_load_lds_dwordx4 v[170:171], off
	v_lshl_add_u64 v[170:171], v[244:245], 0, s[26:27]
	s_mov_b32 m0, s60
	s_nop 0
	global_load_lds_dwordx4 v[170:171], off
	v_lshl_add_u64 v[170:171], v[246:247], 0, s[26:27]
	s_mov_b32 m0, s61
	s_nop 0
	global_load_lds_dwordx4 v[170:171], off
	s_waitcnt vmcnt(8)
	s_waitcnt lgkmcnt(0)
	s_barrier
	s_setprio 1
	v_mfma_f32_16x16x32_bf16 v[62:65], v[136:139], v[198:201], v[62:65]
	v_mfma_f32_16x16x32_bf16 v[58:61], v[144:147], v[198:201], v[58:61]
	v_mfma_f32_16x16x32_bf16 v[46:49], v[136:139], v[220:223], v[46:49]
	v_mfma_f32_16x16x32_bf16 v[42:45], v[144:147], v[220:223], v[42:45]
	v_mfma_f32_16x16x32_bf16 v[30:33], v[136:139], v[228:231], v[30:33]
	v_mfma_f32_16x16x32_bf16 v[26:29], v[144:147], v[228:231], v[26:29]
	v_mfma_f32_16x16x32_bf16 v[14:17], v[136:139], v[236:239], v[14:17]
	v_mfma_f32_16x16x32_bf16 v[10:13], v[144:147], v[236:239], v[10:13]
	v_mfma_f32_16x16x32_bf16 v[62:65], v[140:143], v[216:219], v[62:65]
	v_mfma_f32_16x16x32_bf16 v[58:61], v[148:151], v[216:219], v[58:61]
	v_mfma_f32_16x16x32_bf16 v[46:49], v[140:143], v[224:227], v[46:49]
	v_mfma_f32_16x16x32_bf16 v[42:45], v[148:151], v[224:227], v[42:45]
	v_mfma_f32_16x16x32_bf16 v[30:33], v[140:143], v[232:235], v[30:33]
	v_mfma_f32_16x16x32_bf16 v[26:29], v[148:151], v[232:235], v[26:29]
	v_mfma_f32_16x16x32_bf16 v[14:17], v[140:143], v[240:243], v[14:17]
	v_mfma_f32_16x16x32_bf16 v[10:13], v[148:151], v[240:243], v[10:13]
	v_mfma_f32_16x16x32_bf16 v[54:57], v[152:155], v[198:201], v[54:57]
	v_mfma_f32_16x16x32_bf16 v[50:53], v[190:193], v[198:201], v[50:53]
	v_mfma_f32_16x16x32_bf16 v[38:41], v[152:155], v[220:223], v[38:41]
	v_mfma_f32_16x16x32_bf16 v[34:37], v[190:193], v[220:223], v[34:37]
	v_mfma_f32_16x16x32_bf16 v[22:25], v[152:155], v[228:231], v[22:25]
	v_mfma_f32_16x16x32_bf16 v[18:21], v[190:193], v[228:231], v[18:21]
	v_mfma_f32_16x16x32_bf16 v[6:9], v[152:155], v[236:239], v[6:9]
	v_mfma_f32_16x16x32_bf16 v[2:5], v[190:193], v[236:239], v[2:5]
	v_mfma_f32_16x16x32_bf16 v[54:57], v[186:189], v[216:219], v[54:57]
	v_mfma_f32_16x16x32_bf16 v[50:53], v[194:197], v[216:219], v[50:53]
	v_mfma_f32_16x16x32_bf16 v[38:41], v[186:189], v[224:227], v[38:41]
	v_mfma_f32_16x16x32_bf16 v[34:37], v[194:197], v[224:227], v[34:37]
	v_mfma_f32_16x16x32_bf16 v[22:25], v[186:189], v[232:235], v[22:25]
	v_mfma_f32_16x16x32_bf16 v[18:21], v[194:197], v[232:235], v[18:21]
	v_mfma_f32_16x16x32_bf16 v[6:9], v[186:189], v[240:243], v[6:9]
	v_mfma_f32_16x16x32_bf16 v[2:5], v[194:197], v[240:243], v[2:5]
	s_setprio 0
	s_barrier
	s_add_i32 s69, s69, 2
	s_add_u32 s42, s42, 0x100
	s_addc_u32 s43, s43, 0
	s_add_u32 s67, s67, 0x100
	s_addc_u32 s68, s68, 0
	s_cmp_gt_u32 s69, 29
	s_cbranch_scc0 .LBB0_91
	s_and_b64 vcc, exec, s[16:17]
	s_cbranch_vccz .LBB0_94
	s_barrier
.LBB0_94:
	s_cmp_eq_u32 s98, 0
	s_cbranch_scc1 .Lmy_ik_norm
	s_cmp_eq_u32 s98, 2
	s_cbranch_scc1 .Lmy_ik_prod
	s_branch .Lmy_ik_cons
.Lmy_ik_prod:
	s_lshr_b32 s100, s2, 1
	s_lshl_b32 s100, s100, 18
	s_add_u32 s100, s76, s100
	s_addc_u32 s101, s77, 0
	s_add_u32 s100, s100, 0x1a900000
	s_addc_u32 s101, s101, 0
	v_readfirstlane_b32 s99, v164
	s_lshr_b32 s99, s99, 6
	s_lshl_b32 s99, s99, 15
	s_add_u32 s100, s100, s99
	s_addc_u32 s101, s101, 0
	v_lshlrev_b32_e32 v250, 4, v202
	global_store_dwordx4 v250, v[132:135], s[100:101] sc0 sc1
	global_store_dwordx4 v250, v[128:131], s[100:101] offset:1024 sc0 sc1
	global_store_dwordx4 v250, v[116:119], s[100:101] offset:2048 sc0 sc1
	global_store_dwordx4 v250, v[106:109], s[100:101] offset:3072 sc0 sc1
	s_add_u32 s100, s100, 0x1000
	s_addc_u32 s101, s101, 0
	global_store_dwordx4 v250, v[94:97], s[100:101] sc0 sc1
	global_store_dwordx4 v250, v[90:93], s[100:101] offset:1024 sc0 sc1
	global_store_dwordx4 v250, v[78:81], s[100:101] offset:2048 sc0 sc1
	global_store_dwordx4 v250, v[74:77], s[100:101] offset:3072 sc0 sc1
	s_add_u32 s100, s100, 0x1000
	s_addc_u32 s101, s101, 0
	global_store_dwordx4 v250, v[124:127], s[100:101] sc0 sc1
	global_store_dwordx4 v250, v[120:123], s[100:101] offset:1024 sc0 sc1
	global_store_dwordx4 v250, v[102:105], s[100:101] offset:2048 sc0 sc1
	global_store_dwordx4 v250, v[98:101], s[100:101] offset:3072 sc0 sc1
	s_add_u32 s100, s100, 0x1000
	s_addc_u32 s101, s101, 0
	global_store_dwordx4 v250, v[86:89], s[100:101] sc0 sc1
	global_store_dwordx4 v250, v[82:85], s[100:101] offset:1024 sc0 sc1
	global_store_dwordx4 v250, v[70:73], s[100:101] offset:2048 sc0 sc1
	global_store_dwordx4 v250, v[66:69], s[100:101] offset:3072 sc0 sc1
	s_add_u32 s100, s100, 0x1000
	s_addc_u32 s101, s101, 0
	global_store_dwordx4 v250, v[62:65], s[100:101] sc0 sc1
	global_store_dwordx4 v250, v[58:61], s[100:101] offset:1024 sc0 sc1
	global_store_dwordx4 v250, v[46:49], s[100:101] offset:2048 sc0 sc1
	global_store_dwordx4 v250, v[42:45], s[100:101] offset:3072 sc0 sc1
	s_add_u32 s100, s100, 0x1000
	s_addc_u32 s101, s101, 0
	global_store_dwordx4 v250, v[30:33], s[100:101] sc0 sc1
	global_store_dwordx4 v250, v[26:29], s[100:101] offset:1024 sc0 sc1
	global_store_dwordx4 v250, v[14:17], s[100:101] offset:2048 sc0 sc1
	global_store_dwordx4 v250, v[10:13], s[100:101] offset:3072 sc0 sc1
	s_add_u32 s100, s100, 0x1000
	s_addc_u32 s101, s101, 0
	global_store_dwordx4 v250, v[54:57], s[100:101] sc0 sc1
	global_store_dwordx4 v250, v[50:53], s[100:101] offset:1024 sc0 sc1
	global_store_dwordx4 v250, v[38:41], s[100:101] offset:2048 sc0 sc1
	global_store_dwordx4 v250, v[34:37], s[100:101] offset:3072 sc0 sc1
	s_add_u32 s100, s100, 0x1000
	s_addc_u32 s101, s101, 0
	global_store_dwordx4 v250, v[22:25], s[100:101] sc0 sc1
	global_store_dwordx4 v250, v[18:21], s[100:101] offset:1024 sc0 sc1
	global_store_dwordx4 v250, v[6:9], s[100:101] offset:2048 sc0 sc1
	global_store_dwordx4 v250, v[2:5], s[100:101] offset:3072 sc0 sc1
	s_waitcnt vmcnt(0)
	s_barrier
	v_cmp_eq_u32_e32 vcc, 0, v164
	s_and_saveexec_b64 s[100:101], vcc
	s_cbranch_execz .Lmy_ik_pflag
	s_lshr_b32 s99, s2, 1
	s_lshl_b32 s99, s99, 2
	v_mov_b32_e32 v250, s99
	v_mov_b32_e32 v251, 1
	global_atomic_add v250, v251, s[76:77] offset:256 sc1

.Lmy_ik_spin:
	global_load_dword v251, v250, s[76:77] offset:256 sc1
	s_waitcnt vmcnt(0)
	v_readfirstlane_b32 vcc_lo, v251
	s_cmp_lg_u32 vcc_lo, 0
	s_cbranch_scc1 .Lmy_ik_cgot
	s_sleep 1
	s_add_i32 s99, s99, 1
	s_cmpk_lt_u32 s99, 0x4000
	s_cbranch_scc1 .Lmy_ik_spin
.Lmy_ik_cgot:
	global_store_dword v250, v0, s[76:77] offset:256 sc1
.Lmy_ik_cgot2:
	s_or_b64 exec, exec, s[100:101]
	s_waitcnt vmcnt(0)
	s_barrier
	buffer_inv sc1
	s_lshr_b32 s100, s2, 1
	s_lshl_b32 s100, s100, 18
	s_add_u32 s100, s76, s100
	s_addc_u32 s101, s77, 0
	s_add_u32 s100, s100, 0x1a900000
	s_addc_u32 s101, s101, 0
	v_readfirstlane_b32 s99, v164
	s_lshr_b32 s99, s99, 6
	s_lshl_b32 s99, s99, 15
	s_add_u32 s100, s100, s99
	s_addc_u32 s101, s101, 0
	v_lshlrev_b32_e32 v250, 4, v202
	global_load_dwordx4 v[216:219], v250, s[100:101] sc0 sc1
	global_load_dwordx4 v[220:223], v250, s[100:101] offset:1024 sc0 sc1
	global_load_dwordx4 v[224:227], v250, s[100:101] offset:2048 sc0 sc1
	global_load_dwordx4 v[228:231], v250, s[100:101] offset:3072 sc0 sc1
	s_add_u32 s100, s100, 0x1000
	s_addc_u32 s101, s101, 0
	global_load_dwordx4 v[232:235], v250, s[100:101] sc0 sc1
	global_load_dwordx4 v[236:239], v250, s[100:101] offset:1024 sc0 sc1
	global_load_dwordx4 v[240:243], v250, s[100:101] offset:2048 sc0 sc1
	global_load_dwordx4 v[136:139], v250, s[100:101] offset:3072 sc0 sc1
	s_add_u32 s100, s100, 0x1000
	s_addc_u32 s101, s101, 0
	s_waitcnt vmcnt(7)
	v_pk_add_f32 v[132:133], v[132:133], v[216:217]
	v_pk_add_f32 v[134:135], v[134:135], v[218:219]
	s_waitcnt vmcnt(6)
	v_pk_add_f32 v[128:129], v[128:129], v[220:221]
	v_pk_add_f32 v[130:131], v[130:131], v[222:223]
	s_waitcnt vmcnt(5)
	v_pk_add_f32 v[116:117], v[116:117], v[224:225]
	v_pk_add_f32 v[118:119], v[118:119], v[226:227]
	s_waitcnt vmcnt(4)
	v_pk_add_f32 v[106:107], v[106:107], v[228:229]
	v_pk_add_f32 v[108:109], v[108:109], v[230:231]
	s_waitcnt vmcnt(3)
	v_pk_add_f32 v[94:95], v[94:95], v[232:233]
	v_pk_add_f32 v[96:97], v[96:97], v[234:235]
	s_waitcnt vmcnt(2)
	v_pk_add_f32 v[90:91], v[90:91], v[236:237]
	v_pk_add_f32 v[92:93], v[92:93], v[238:239]
	s_waitcnt vmcnt(1)
	v_pk_add_f32 v[78:79], v[78:79], v[240:241]
	v_pk_add_f32 v[80:81], v[80:81], v[242:243]
	s_waitcnt vmcnt(0)
	v_pk_add_f32 v[74:75], v[74:75], v[136:137]
	v_pk_add_f32 v[76:77], v[76:77], v[138:139]
	global_load_dwordx4 v[216:219], v250, s[100:101] sc0 sc1
	global_load_dwordx4 v[220:223], v250, s[100:101] offset:1024 sc0 sc1
	global_load_dwordx4 v[224:227], v250, s[100:101] offset:2048 sc0 sc1
	global_load_dwordx4 v[228:231], v250, s[100:101] offset:3072 sc0 sc1
	s_add_u32 s100, s100, 0x1000
	s_addc_u32 s101, s101, 0
	global_load_dwordx4 v[232:235], v250, s[100:101] sc0 sc1
	global_load_dwordx4 v[236:239], v250, s[100:101] offset:1024 sc0 sc1
	global_load_dwordx4 v[240:243], v250, s[100:101] offset:2048 sc0 sc1
	global_load_dwordx4 v[136:139], v250, s[100:101] offset:3072 sc0 sc1
	s_add_u32 s100, s100, 0x1000
	s_addc_u32 s101, s101, 0
	s_waitcnt vmcnt(7)
	v_pk_add_f32 v[124:125], v[124:125], v[216:217]
	v_pk_add_f32 v[126:127], v[126:127], v[218:219]
	s_waitcnt vmcnt(6)
	v_pk_add_f32 v[120:121], v[120:121], v[220:221]
	v_pk_add_f32 v[122:123], v[122:123], v[222:223]
	s_waitcnt vmcnt(5)
	v_pk_add_f32 v[102:103], v[102:103], v[224:225]
	v_pk_add_f32 v[104:105], v[104:105], v[226:227]
	s_waitcnt vmcnt(4)
	v_pk_add_f32 v[98:99], v[98:99], v[228:229]
	v_pk_add_f32 v[100:101], v[100:101], v[230:231]
	s_waitcnt vmcnt(3)
	v_pk_add_f32 v[86:87], v[86:87], v[232:233]
	v_pk_add_f32 v[88:89], v[88:89], v[234:235]
	s_waitcnt vmcnt(2)
	v_pk_add_f32 v[82:83], v[82:83], v[236:237]
	v_pk_add_f32 v[84:85], v[84:85], v[238:239]
	s_waitcnt vmcnt(1)
	v_pk_add_f32 v[70:71], v[70:71], v[240:241]
	v_pk_add_f32 v[72:73], v[72:73], v[242:243]
	s_waitcnt vmcnt(0)
	v_pk_add_f32 v[66:67], v[66:67], v[136:137]
	v_pk_add_f32 v[68:69], v[68:69], v[138:139]
	global_load_dwordx4 v[216:219], v250, s[100:101] sc0 sc1
	global_load_dwordx4 v[220:223], v250, s[100:101] offset:1024 sc0 sc1
	global_load_dwordx4 v[224:227], v250, s[100:101] offset:2048 sc0 sc1
	global_load_dwordx4 v[228:231], v250, s[100:101] offset:3072 sc0 sc1
	s_add_u32 s100, s100, 0x1000
	s_addc_u32 s101, s101, 0
	global_load_dwordx4 v[232:235], v250, s[100:101] sc0 sc1
	global_load_dwordx4 v[236:239], v250, s[100:101] offset:1024 sc0 sc1
	global_load_dwordx4 v[240:243], v250, s[100:101] offset:2048 sc0 sc1
	global_load_dwordx4 v[136:139], v250, s[100:101] offset:3072 sc0 sc1
	s_add_u32 s100, s100, 0x1000
	s_addc_u32 s101, s101, 0
	s_waitcnt vmcnt(7)
	v_pk_add_f32 v[62:63], v[62:63], v[216:217]
	v_pk_add_f32 v[64:65], v[64:65], v[218:219]
	s_waitcnt vmcnt(6)
	v_pk_add_f32 v[58:59], v[58:59], v[220:221]
	v_pk_add_f32 v[60:61], v[60:61], v[222:223]
	s_waitcnt vmcnt(5)
	v_pk_add_f32 v[46:47], v[46:47], v[224:225]
	v_pk_add_f32 v[48:49], v[48:49], v[226:227]
	s_waitcnt vmcnt(4)
	v_pk_add_f32 v[42:43], v[42:43], v[228:229]
	v_pk_add_f32 v[44:45], v[44:45], v[230:231]
	s_waitcnt vmcnt(3)
	v_pk_add_f32 v[30:31], v[30:31], v[232:233]
	v_pk_add_f32 v[32:33], v[32:33], v[234:235]
	s_waitcnt vmcnt(2)
	v_pk_add_f32 v[26:27], v[26:27], v[236:237]
	v_pk_add_f32 v[28:29], v[28:29], v[238:239]
	s_waitcnt vmcnt(1)
	v_pk_add_f32 v[14:15], v[14:15], v[240:241]
	v_pk_add_f32 v[16:17], v[16:17], v[242:243]
	s_waitcnt vmcnt(0)
	v_pk_add_f32 v[10:11], v[10:11], v[136:137]
	v_pk_add_f32 v[12:13], v[12:13], v[138:139]
	global_load_dwordx4 v[216:219], v250, s[100:101] sc0 sc1
	global_load_dwordx4 v[220:223], v250, s[100:101] offset:1024 sc0 sc1
	global_load_dwordx4 v[224:227], v250, s[100:101] offset:2048 sc0 sc1
	global_load_dwordx4 v[228:231], v250, s[100:101] offset:3072 sc0 sc1
	s_add_u32 s100, s100, 0x1000
	s_addc_u32 s101, s101, 0
	global_load_dwordx4 v[232:235], v250, s[100:101] sc0 sc1
	global_load_dwordx4 v[236:239], v250, s[100:101] offset:1024 sc0 sc1
	global_load_dwordx4 v[240:243], v250, s[100:101] offset:2048 sc0 sc1
	global_load_dwordx4 v[136:139], v250, s[100:101] offset:3072 sc0 sc1
	s_waitcnt vmcnt(7)
	v_pk_add_f32 v[54:55], v[54:55], v[216:217]
	v_pk_add_f32 v[56:57], v[56:57], v[218:219]
	s_waitcnt vmcnt(6)
	v_pk_add_f32 v[50:51], v[50:51], v[220:221]
	v_pk_add_f32 v[52:53], v[52:53], v[222:223]
	s_waitcnt vmcnt(5)
	v_pk_add_f32 v[38:39], v[38:39], v[224:225]
	v_pk_add_f32 v[40:41], v[40:41], v[226:227]
	s_waitcnt vmcnt(4)
	v_pk_add_f32 v[34:35], v[34:35], v[228:229]
	v_pk_add_f32 v[36:37], v[36:37], v[230:231]
	s_waitcnt vmcnt(3)
	v_pk_add_f32 v[22:23], v[22:23], v[232:233]
	v_pk_add_f32 v[24:25], v[24:25], v[234:235]
	s_waitcnt vmcnt(2)
	v_pk_add_f32 v[18:19], v[18:19], v[236:237]
	v_pk_add_f32 v[20:21], v[20:21], v[238:239]
	s_waitcnt vmcnt(1)
	v_pk_add_f32 v[6:7], v[6:7], v[240:241]
	v_pk_add_f32 v[8:9], v[8:9], v[242:243]
	s_waitcnt vmcnt(0)
	v_pk_add_f32 v[2:3], v[2:3], v[136:137]
	v_pk_add_f32 v[4:5], v[4:5], v[138:139]
	s_branch .Lmy_ik_norm
